# permlane-swap head-norm reduction also in the ctx GLA run of the scan phase (3 of its 4 groups)
# speedup vs baseline: 1.0120x; 1.0120x over previous
.LBB0_591:
	s_or_b64 exec, exec, s[0:1]
	s_waitcnt vmcnt(15)
	v_lshlrev_b32_e32 v160, 16, v146
	s_waitcnt lgkmcnt(0)
	v_and_b32_e32 v161, 0xffff0000, v146
	v_pk_add_f32 v[160:161], v[96:97], v[160:161]
	v_lshlrev_b32_e32 v96, 16, v147
	v_and_b32_e32 v97, 0xffff0000, v147
	v_pk_add_f32 v[98:99], v[98:99], v[96:97]
	v_pk_mul_f32 v[146:147], v[160:161], v[160:161]
	v_pk_mul_f32 v[200:201], v[98:99], v[98:99]
	s_waitcnt vmcnt(14)
	v_lshlrev_b32_e32 v96, 16, v144
	v_and_b32_e32 v97, 0xffff0000, v144
	v_add_f32_e32 v146, v146, v147
	v_pk_add_f32 v[96:97], v[92:93], v[96:97]
	v_lshlrev_b32_e32 v92, 16, v145
	v_and_b32_e32 v93, 0xffff0000, v145
	v_add_f32_e32 v146, v200, v146
	v_pk_add_f32 v[94:95], v[94:95], v[92:93]
	v_pk_mul_f32 v[92:93], v[96:97], v[96:97]
	v_add_f32_e32 v146, v201, v146
	v_add_f32_e32 v92, v92, v146
	v_pk_mul_f32 v[144:145], v[94:95], v[94:95]
	v_add_f32_e32 v92, v93, v92
	v_add_f32_e32 v92, v144, v92
	v_add_f32_e32 v92, v145, v92
	v_mov_b32_e32 v93, v92
	s_nop 1
	v_permlane16_swap_b32_e32 v93, v92
	s_waitcnt lgkmcnt(0)
	v_add_f32_e32 v92, v92, v93
	v_mov_b32_e32 v93, v92
	s_nop 1
	v_permlane32_swap_b32_e32 v93, v92
	s_and_saveexec_b64 s[0:1], s[6:7]
	s_cbranch_execz .LBB0_593
	s_waitcnt lgkmcnt(0)
	v_add_f32_e32 v92, v92, v93
	ds_write_b32 v181, v92 offset:512
.LBB0_593:
	s_or_b64 exec, exec, s[0:1]
	s_waitcnt vmcnt(13)
	v_lshlrev_b32_e32 v92, 16, v140
	s_waitcnt lgkmcnt(0)
	v_and_b32_e32 v93, 0xffff0000, v140
	v_pk_add_f32 v[88:89], v[88:89], v[92:93]
	v_lshlrev_b32_e32 v92, 16, v141
	v_and_b32_e32 v93, 0xffff0000, v141
	v_pk_add_f32 v[92:93], v[90:91], v[92:93]
	v_pk_mul_f32 v[140:141], v[88:89], v[88:89]
	v_pk_mul_f32 v[144:145], v[92:93], v[92:93]
	s_waitcnt vmcnt(12)
	v_lshlrev_b32_e32 v90, 16, v138
	v_and_b32_e32 v91, 0xffff0000, v138
	v_add_f32_e32 v140, v140, v141
	v_pk_add_f32 v[90:91], v[84:85], v[90:91]
	v_lshlrev_b32_e32 v84, 16, v139
	v_and_b32_e32 v85, 0xffff0000, v139
	v_add_f32_e32 v140, v144, v140
	v_pk_add_f32 v[86:87], v[86:87], v[84:85]
	v_pk_mul_f32 v[84:85], v[90:91], v[90:91]
	v_add_f32_e32 v140, v145, v140
	v_add_f32_e32 v84, v84, v140
	v_pk_mul_f32 v[138:139], v[86:87], v[86:87]
	v_add_f32_e32 v84, v85, v84
	v_add_f32_e32 v84, v138, v84
	v_add_f32_e32 v84, v139, v84
	v_mov_b32_e32 v85, v84
	s_nop 1
	v_permlane16_swap_b32_e32 v85, v84
	s_waitcnt lgkmcnt(0)
	v_add_f32_e32 v84, v84, v85
	v_mov_b32_e32 v85, v84
	s_nop 1
	v_permlane32_swap_b32_e32 v85, v84
	s_and_saveexec_b64 s[0:1], s[6:7]
	s_cbranch_execz .LBB0_595
	s_waitcnt lgkmcnt(0)
	v_add_f32_e32 v84, v84, v85
	ds_write_b32 v181, v84 offset:1024
.LBB0_595:
	s_or_b64 exec, exec, s[0:1]
	s_waitcnt vmcnt(11)
	v_lshlrev_b32_e32 v84, 16, v134
	s_waitcnt lgkmcnt(0)
	v_and_b32_e32 v85, 0xffff0000, v134
	v_pk_add_f32 v[84:85], v[80:81], v[84:85]
	v_lshlrev_b32_e32 v80, 16, v135
	v_and_b32_e32 v81, 0xffff0000, v135
	v_pk_add_f32 v[82:83], v[82:83], v[80:81]
	v_pk_mul_f32 v[134:135], v[84:85], v[84:85]
	v_pk_mul_f32 v[138:139], v[82:83], v[82:83]
	s_waitcnt vmcnt(10)
	v_lshlrev_b32_e32 v80, 16, v132
	v_and_b32_e32 v81, 0xffff0000, v132
	v_add_f32_e32 v134, v134, v135
	v_pk_add_f32 v[80:81], v[76:77], v[80:81]
	v_lshlrev_b32_e32 v76, 16, v133
	v_and_b32_e32 v77, 0xffff0000, v133
	v_add_f32_e32 v134, v138, v134
	v_pk_add_f32 v[76:77], v[78:79], v[76:77]
	v_pk_mul_f32 v[78:79], v[80:81], v[80:81]
	v_add_f32_e32 v134, v139, v134
	v_add_f32_e32 v78, v78, v134
	v_pk_mul_f32 v[132:133], v[76:77], v[76:77]
	v_add_f32_e32 v78, v79, v78
	v_add_f32_e32 v78, v132, v78
	v_add_f32_e32 v78, v133, v78
	v_mov_b32_e32 v79, v78
	s_nop 1
	v_permlane16_swap_b32_e32 v79, v78
	s_waitcnt lgkmcnt(0)
	v_add_f32_e32 v78, v78, v79
	v_mov_b32_e32 v79, v78
	s_nop 1
	v_permlane32_swap_b32_e32 v79, v78
	s_and_saveexec_b64 s[0:1], s[6:7]
	s_cbranch_execz .LBB0_579
	s_waitcnt lgkmcnt(0)
	v_add_f32_e32 v78, v78, v79
	ds_write_b32 v181, v78 offset:1536
	s_branch .LBB0_579
